# MLA fast path: V fragment reads as two ds_read_b64 (64-bank addressing) instead of ds_read2_b64 (2-way bank conflicts)
# baseline (speedup 1.0000x reference)
; #define MFMA32(a, b, c) __builtin_amdgcn_mfma_f32_32x32x16_bf16((a), (b), (c), 0, 0, 0)
; DI uint32_t pack2(float a, float b) { f2_t v = {a, b}; bf2_t r = __builtin_convertvector(v, bf2_t); return __builtin_bit_cast(uint32_t, r); }
; DI float xmax32(float v) { unsigned u = __float_as_uint(v); auto r = __builtin_amdgcn_permlane32_swap(u, u, false, false); return fmaxf(__uint_as_float(r[0]), __uint_as_float(r[1])); }
; template <int MODE, bool FAST>
; DI void attn_item(const Params& p, int layer, int b, int hd, int qt, char* smem) {
;     ...
; #pragma unroll
;         for (int ks = 0; ks < KS; ++ks) {
;           bf16x8 a = *(const bf16x8*)&sK[buf][sub * 32 + r][ks * 16 + 8 * h];
;           s = MFMA32(a, qf[ks], s);
;         }
;     ...
;           if (fastsm) {
;             float ls = 0.f;
; #pragma unroll
;             for (int i = 0; i < 16; ++i) { pv[i] = fexp2(u[i]); ls += pv[i]; }
;             lrun += ls;
;           } else {
;           float mx = u[0];
; #pragma unroll
;           for (int i = 1; i < 16; ++i) mx = fmaxf(mx, u[i]);
;           mx = xmax32(mx);
;           const float mnew = fmaxf(mrun, mx);
;           const float muse = (mnew == -INFINITY) ? 0.f : mnew;
;           const float alpha = fexp2(mrun - muse);
;           float ls = 0.f;
; #pragma unroll
;           for (int i = 0; i < 16; ++i) { pv[i] = fexp2(u[i] - muse); ls += pv[i]; }
;           lrun = lrun * alpha + ls;
;           mrun = mnew;
;           if (__any(alpha != 1.f)) {
; #pragma unroll
;             for (int i = 0; i < 16; ++i) { o[0][i] *= alpha; o[1][i] *= alpha; }
;           }
;           }
;         }
; #pragma unroll
;         for (int sidx = 0; sidx < 2; ++sidx) {
;           uint4 pk4 = make_uint4(pack2(pv[8 * sidx], pv[8 * sidx + 1]), pack2(pv[8 * sidx + 2], pv[8 * sidx + 3]),
;                                  pack2(pv[8 * sidx + 4], pv[8 * sidx + 5]), pack2(pv[8 * sidx + 6], pv[8 * sidx + 7]));
;           bf16x8 pf = __builtin_bit_cast(bf16x8, pk4);
; #pragma unroll
;           for (int dt = 0; dt < 2; ++dt) {
;             const u16* vp = &sV[buf][dt * 32 + r][sub * 32 + 16 * sidx + 4 * h];
;             uint2 lo = *(const uint2*)vp;
;             uint2 hi = *(const uint2*)(vp + 8);
;             bf16x8 va = __builtin_bit_cast(bf16x8, make_uint4(lo.x, lo.y, hi.x, hi.y));
;             o[dt] = MFMA32(va, pf, o[dt]);
;           }
;         }
.Lmla_fast:
	ds_read_b128 v[6:9], v4
	ds_read_b128 v[10:13], v4 offset:32
	ds_read_b128 v[14:17], v4 offset:64
	ds_read_b128 v[130:133], v4 offset:96
	ds_read_b128 v[156:159], v4 offset:128
	ds_read_b128 v[170:173], v4 offset:160
	v_add_u32_e32 v5, 0x6800, v2
	v_add_u32_e32 v160, 0x7800, v2
	s_waitcnt lgkmcnt(5)
	v_mfma_f32_32x32x16_bf16 v[50:65], v[6:9], v[74:77], 0
	ds_read_b128 v[6:9], v4 offset:6656
	s_waitcnt lgkmcnt(5)
	v_mfma_f32_32x32x16_bf16 v[50:65], v[10:13], v[82:85], v[50:65]
	ds_read_b128 v[10:13], v4 offset:6688
	s_waitcnt lgkmcnt(5)
	v_mfma_f32_32x32x16_bf16 v[50:65], v[14:17], v[86:89], v[50:65]
	ds_read_b128 v[14:17], v4 offset:6720
	s_waitcnt lgkmcnt(5)
	v_mfma_f32_32x32x16_bf16 v[50:65], v[130:133], v[90:93], v[50:65]
	ds_read_b128 v[130:133], v4 offset:6752
	s_waitcnt lgkmcnt(5)
	v_mfma_f32_32x32x16_bf16 v[50:65], v[156:159], v[94:97], v[50:65]
	ds_read_b128 v[156:159], v4 offset:6784
	s_waitcnt lgkmcnt(5)
	v_mfma_f32_32x32x16_bf16 v[50:65], v[170:173], v[78:81], v[50:65]
	ds_read_b128 v[170:173], v4 offset:6816
	ds_read_b64 v[174:175], v5
	ds_read_b64 v[176:177], v5 offset:16
	ds_read_b64 v[240:241], v160 offset:512
	ds_read_b64 v[242:243], v160 offset:528
	ds_read_b64 v[230:231], v5 offset:32
	ds_read_b64 v[232:233], v5 offset:48
	ds_read_b64 v[244:245], v160 offset:544
	ds_read_b64 v[246:247], v160 offset:560
	s_waitcnt lgkmcnt(13)
	v_mfma_f32_32x32x16_bf16 v[186:201], v[6:9], v[74:77], 0
	s_waitcnt lgkmcnt(12)
	v_mfma_f32_32x32x16_bf16 v[186:201], v[10:13], v[82:85], v[186:201]
	s_nop 3
	v_exp_f32_e32 v50, v50
	v_exp_f32_e32 v51, v51
	v_exp_f32_e32 v52, v52
	v_exp_f32_e32 v53, v53
	s_waitcnt lgkmcnt(11)
	v_mfma_f32_32x32x16_bf16 v[186:201], v[14:17], v[86:89], v[186:201]
	v_exp_f32_e32 v54, v54
	v_exp_f32_e32 v55, v55
	v_exp_f32_e32 v56, v56
	v_exp_f32_e32 v57, v57
	v_add_f32_e32 v161, v50, v51
	v_add_f32_e32 v164, v52, v53
	s_waitcnt lgkmcnt(10)
	v_mfma_f32_32x32x16_bf16 v[186:201], v[130:133], v[90:93], v[186:201]
	v_exp_f32_e32 v58, v58
	v_exp_f32_e32 v59, v59
	v_exp_f32_e32 v60, v60
	v_exp_f32_e32 v61, v61
	v_add_f32_e32 v161, v161, v54
	v_add_f32_e32 v164, v164, v55
	v_add_f32_e32 v161, v161, v56
	v_add_f32_e32 v164, v164, v57
	s_waitcnt lgkmcnt(9)
	v_mfma_f32_32x32x16_bf16 v[186:201], v[156:159], v[94:97], v[186:201]
	v_exp_f32_e32 v62, v62
	v_exp_f32_e32 v63, v63
	v_exp_f32_e32 v64, v64
	v_exp_f32_e32 v65, v65
	v_add_f32_e32 v161, v161, v58
	v_add_f32_e32 v164, v164, v59
	v_add_f32_e32 v161, v161, v60
	v_add_f32_e32 v164, v164, v61
	s_waitcnt lgkmcnt(8)
	v_mfma_f32_32x32x16_bf16 v[186:201], v[170:173], v[78:81], v[186:201]
	v_add_f32_e32 v161, v161, v62
	v_add_f32_e32 v164, v164, v63
	v_add_f32_e32 v161, v161, v64
	v_add_f32_e32 v164, v164, v65
	ds_read_b64 v[6:7], v5 offset:64
	ds_read_b64 v[8:9], v5 offset:80
	ds_read_b64 v[10:11], v160 offset:576
	ds_read_b64 v[12:13], v160 offset:592
	ds_read_b64 v[14:15], v5 offset:96
	ds_read_b64 v[16:17], v5 offset:112
	ds_read_b64 v[130:131], v160 offset:608
	ds_read_b64 v[132:133], v160 offset:624
	v_add_f32_e32 v161, v161, v164
	v_add_f32_e32 v113, v113, v161
	v_cvt_pk_bf16_f32 v50, v50, v51
	v_cvt_pk_bf16_f32 v51, v52, v53
	v_cvt_pk_bf16_f32 v52, v54, v55
	v_cvt_pk_bf16_f32 v53, v56, v57
	v_cvt_pk_bf16_f32 v54, v58, v59
	v_cvt_pk_bf16_f32 v55, v60, v61
	v_cvt_pk_bf16_f32 v56, v62, v63
	v_cvt_pk_bf16_f32 v57, v64, v65
	s_nop 1
	s_waitcnt lgkmcnt(14)
	v_mfma_f32_32x32x16_bf16 v[34:49], v[174:177], v[50:53], v[34:49]
	v_exp_f32_e32 v186, v186
	v_exp_f32_e32 v187, v187
	v_exp_f32_e32 v188, v188
	v_exp_f32_e32 v189, v189
	s_waitcnt lgkmcnt(12)
	v_mfma_f32_32x32x16_bf16 v[18:33], v[240:243], v[50:53], v[18:33]
	v_exp_f32_e32 v190, v190
	v_exp_f32_e32 v191, v191
	v_exp_f32_e32 v192, v192
	v_exp_f32_e32 v193, v193
	v_add_f32_e32 v161, v186, v187
	v_add_f32_e32 v164, v188, v189
	s_waitcnt lgkmcnt(10)
	v_mfma_f32_32x32x16_bf16 v[34:49], v[230:233], v[54:57], v[34:49]
	v_exp_f32_e32 v194, v194
	v_exp_f32_e32 v195, v195
	v_exp_f32_e32 v196, v196
	v_exp_f32_e32 v197, v197
	v_add_f32_e32 v161, v161, v190
	v_add_f32_e32 v164, v164, v191
	v_add_f32_e32 v161, v161, v192
	v_add_f32_e32 v164, v164, v193
	s_waitcnt lgkmcnt(8)
	v_mfma_f32_32x32x16_bf16 v[18:33], v[244:247], v[54:57], v[18:33]
	v_exp_f32_e32 v198, v198
	v_exp_f32_e32 v199, v199
	v_exp_f32_e32 v200, v200
	v_exp_f32_e32 v201, v201
	v_add_f32_e32 v161, v161, v194
	v_add_f32_e32 v164, v164, v195
	v_add_f32_e32 v161, v161, v196
	v_add_f32_e32 v164, v164, v197
	v_add_f32_e32 v161, v161, v198
	v_add_f32_e32 v164, v164, v199
	v_add_f32_e32 v161, v161, v200
	v_add_f32_e32 v164, v164, v201
	v_add_f32_e32 v161, v161, v164
	v_add_f32_e32 v113, v113, v161
	v_cvt_pk_bf16_f32 v186, v186, v187
	v_cvt_pk_bf16_f32 v187, v188, v189
	v_cvt_pk_bf16_f32 v188, v190, v191
	v_cvt_pk_bf16_f32 v189, v192, v193
	v_cvt_pk_bf16_f32 v190, v194, v195
	v_cvt_pk_bf16_f32 v191, v196, v197
	v_cvt_pk_bf16_f32 v192, v198, v199
	v_cvt_pk_bf16_f32 v193, v200, v201
	s_nop 1
	s_waitcnt lgkmcnt(6)
	v_mfma_f32_32x32x16_bf16 v[34:49], v[6:9], v[186:189], v[34:49]
	s_waitcnt lgkmcnt(4)
	v_mfma_f32_32x32x16_bf16 v[18:33], v[10:13], v[186:189], v[18:33]
	s_waitcnt lgkmcnt(2)
	v_mfma_f32_32x32x16_bf16 v[34:49], v[14:17], v[190:193], v[34:49]
	s_waitcnt lgkmcnt(0)
	v_mfma_f32_32x32x16_bf16 v[18:33], v[130:133], v[190:193], v[18:33]
	s_branch .LBB0_109
